# v63 + nt on the once-read f32 weight loads of the in-phase weight conversions (P1: w_in, P3: up/out/FFN2 weights)
# speedup vs baseline: 1.0223x; 1.0060x over previous
.LBB0_148:
	s_cmpk_gt_i32 s16, 0x57f
	s_mov_b64 s[0:1], -1
	s_cbranch_scc0 .LBB0_214
	s_cmpk_gt_u32 s16, 0xaff
	s_cbranch_scc0 .LBB0_203
	s_cmpk_gt_u32 s16, 0x107f
	s_cbranch_scc0 .LBB0_200
	s_add_i32 s0, s16, 0xef80
	s_bfe_u32 s1, s0, 0xd0003
	s_mulk_i32 s1, 0xc31
	s_lshr_b32 s1, s1, 16
	s_mul_i32 s6, s1, 0xa8
	s_sub_i32 s18, s0, s6
	s_lshl_b32 s14, s1, 6
	v_or_b32_e32 v53, s14, v34
	s_lshl_b32 s0, s18, 7
	s_and_b32 s10, s0, 0x3ff80
	v_mul_u32_u24_e32 v4, 0x1500, v53
	v_lshl_add_u64 v[2:3], v[44:45], 0, s[10:11]
	v_lshlrev_b32_e32 v36, 2, v4
	v_lshl_add_u64 v[2:3], v[2:3], 0, v[36:37]
	s_mov_b32 s0, 0x2a000
	v_add_co_u32_e32 v4, vcc, s0, v2
	s_mov_b32 s0, 0x54000
	s_nop 0
	v_addc_co_u32_e32 v5, vcc, 0, v3, vcc
	global_load_dwordx4 v[26:29], v[2:3], off nt
	global_load_dwordx4 v[30:33], v[4:5], off nt
	v_add_co_u32_e32 v4, vcc, s0, v2
	s_mov_b32 s0, 0x7e000
	s_nop 0
	v_addc_co_u32_e32 v5, vcc, 0, v3, vcc
	v_add_co_u32_e32 v6, vcc, s0, v2
	v_mov_b32_e32 v52, 1.0
	s_nop 0
	v_addc_co_u32_e32 v7, vcc, 0, v3, vcc
	global_load_dwordx4 v[18:21], v[4:5], off nt
	global_load_dwordx4 v[22:25], v[6:7], off nt
	v_add_co_u32_e32 v4, vcc, s26, v2
	v_add_lshl_u32 v36, v34, s14, 2
	s_nop 0
	v_addc_co_u32_e32 v5, vcc, 0, v3, vcc
	v_add_co_u32_e32 v6, vcc, 0xd2000, v2
	v_mov_b32_e32 v59, 1.0
	s_nop 0
	v_addc_co_u32_e32 v7, vcc, 0, v3, vcc
	global_load_dwordx4 v[10:13], v[4:5], off nt
	global_load_dwordx4 v[14:17], v[6:7], off nt
	v_add_co_u32_e32 v4, vcc, 0xfc000, v2
	s_nop 1
	v_addc_co_u32_e32 v5, vcc, 0, v3, vcc
	v_add_co_u32_e32 v6, vcc, 0x126000, v2
	s_nop 1
	v_addc_co_u32_e32 v7, vcc, 0, v3, vcc
	global_load_dwordx4 v[2:5], v[4:5], off nt
	s_nop 0
	global_load_dwordx4 v[6:9], v[6:7], off nt
	s_and_b64 vcc, exec, s[4:5]
	s_cbranch_vccnz .LBB0_153
	v_lshlrev_b32_e32 v53, 2, v53
	global_load_dword v60, v53, s[80:81]
	global_load_dword v59, v36, s[80:81] offset:32
	s_waitcnt vmcnt(1)
	v_pk_mul_f32 v[26:27], v[26:27], v[60:61] op_sel_hi:[1,0]
	v_pk_mul_f32 v[28:29], v[28:29], v[60:61] op_sel_hi:[1,0]

.LBB0_200:
	s_and_b64 vcc, exec, s[0:1]
	s_cbranch_vccz .LBB0_202
	s_add_i32 s1, s20, 0xfffea000
	s_and_b32 s0, s24, 0xfc0
	s_and_b32 s1, s1, 0x3e0
	v_or_b32_e32 v4, s0, v34
	s_lshl_b32 s10, s1, 2
	v_lshl_add_u64 v[2:3], v[46:47], 0, s[10:11]
	v_lshlrev_b32_e32 v36, 12, v4
	v_lshl_add_u64 v[26:27], v[2:3], 0, v[36:37]
	v_add_co_u32_e32 v6, vcc, s29, v26
	v_add_u32_e32 v59, v54, v55
	s_nop 0
	v_addc_co_u32_e32 v7, vcc, 0, v27, vcc
	v_add_co_u32_e32 v10, vcc, s30, v26
	global_load_dwordx4 v[2:5], v[26:27], off nt
	s_nop 0
	global_load_dwordx4 v[6:9], v[6:7], off nt
	v_addc_co_u32_e32 v11, vcc, 0, v27, vcc
	v_add_co_u32_e32 v14, vcc, s31, v26
	v_or_b32_e32 v36, s1, v34
	s_nop 0
	v_addc_co_u32_e32 v15, vcc, 0, v27, vcc
	v_add_co_u32_e32 v18, vcc, s36, v26
	global_load_dwordx4 v[10:13], v[10:11], off nt
	s_nop 0
	global_load_dwordx4 v[14:17], v[14:15], off nt
	v_addc_co_u32_e32 v19, vcc, 0, v27, vcc
	v_add_co_u32_e32 v22, vcc, s37, v26
	v_add_u32_e32 v64, 0x840, v59
	s_nop 0
	v_addc_co_u32_e32 v23, vcc, 0, v27, vcc
	v_add_co_u32_e32 v28, vcc, s38, v26
	global_load_dwordx4 v[18:21], v[18:19], off nt
	s_nop 0
	global_load_dwordx4 v[22:25], v[22:23], off nt
	v_addc_co_u32_e32 v29, vcc, 0, v27, vcc
	v_add_co_u32_e32 v30, vcc, s39, v26
	v_add_u32_e32 v65, 0x850, v59
	s_nop 0
	v_addc_co_u32_e32 v31, vcc, 0, v27, vcc
	global_load_dwordx4 v[26:29], v[28:29], off nt
	s_nop 0
	global_load_dwordx4 v[30:33], v[30:31], off nt
	v_add_u32_e32 v66, 0x1080, v59
	v_add_u32_e32 v67, 0x1090, v59
	v_or_b32_e32 v52, s1, v56
	s_lshl_b32 s10, s0, 1
	v_mul_u32_u24_e32 v36, 0xb00, v36
	v_mul_u32_u24_e32 v62, 0xb00, v52
	v_lshl_add_u64 v[52:53], v[40:41], 0, s[10:11]
	v_lshlrev_b32_e32 v36, 1, v36
	v_lshl_add_u64 v[60:61], v[52:53], 0, v[36:37]
	v_lshlrev_b32_e32 v36, 1, v62
	v_lshl_add_u64 v[62:63], v[52:53], 0, v[36:37]
	s_waitcnt vmcnt(6)
	ds_write2_b32 v1, v2, v6 offset1:8
	ds_write2_b32 v1, v3, v7 offset0:66 offset1:74
	ds_write2_b32 v1, v4, v8 offset0:132 offset1:140
	ds_write2_b32 v1, v5, v9 offset0:198 offset1:206
	s_waitcnt vmcnt(4)
	ds_write2_b32 v1, v10, v14 offset0:16 offset1:24
	ds_write2_b32 v1, v11, v15 offset0:82 offset1:90
	ds_write2_b32 v1, v12, v16 offset0:148 offset1:156
	ds_write2_b32 v1, v13, v17 offset0:214 offset1:222
	s_waitcnt vmcnt(2)
	ds_write2_b32 v1, v18, v22 offset0:32 offset1:40
	ds_write2_b32 v1, v19, v23 offset0:98 offset1:106
	ds_write2_b32 v1, v20, v24 offset0:164 offset1:172
	ds_write2_b32 v1, v21, v25 offset0:230 offset1:238
	s_waitcnt vmcnt(0)
	ds_write2_b32 v1, v26, v30 offset0:48 offset1:56
	ds_write2_b32 v1, v27, v31 offset0:114 offset1:122
	ds_write2_b32 v1, v28, v32 offset0:180 offset1:188
	ds_write2_b32 v1, v29, v33 offset0:246 offset1:254
	s_waitcnt lgkmcnt(0)
	ds_read2_b64 v[2:5], v59 offset1:1
	ds_read2_b64 v[6:9], v59 offset0:2 offset1:3
	ds_read2_b64 v[10:13], v64 offset1:1
	ds_read2_b64 v[14:17], v65 offset1:1
	ds_read2_b64 v[18:21], v66 offset1:1
	ds_read2_b64 v[22:25], v67 offset1:1
	s_waitcnt lgkmcnt(5)
	v_cvt_pk_bf16_f32 v2, v2, v3
	v_cvt_pk_bf16_f32 v3, v4, v5
	s_waitcnt lgkmcnt(4)
	v_cvt_pk_bf16_f32 v4, v6, v7
	v_cvt_pk_bf16_f32 v5, v8, v9
	s_waitcnt lgkmcnt(3)
	v_cvt_pk_bf16_f32 v6, v10, v11
	v_cvt_pk_bf16_f32 v7, v12, v13
	s_waitcnt lgkmcnt(2)
	v_cvt_pk_bf16_f32 v8, v14, v15
	v_cvt_pk_bf16_f32 v9, v16, v17
	global_store_dwordx4 v[60:61], v[2:5], off sc0 sc1
	global_store_dwordx4 v[62:63], v[6:9], off sc0 sc1
	s_waitcnt lgkmcnt(1)
	v_cvt_pk_bf16_f32 v10, v18, v19
	v_or_b32_e32 v2, s1, v57
	v_mul_u32_u24_e32 v2, 0xb00, v2
	v_lshlrev_b32_e32 v36, 1, v2
	v_add_u32_e32 v2, 0x18c0, v59
	v_add_u32_e32 v6, 0x18d0, v59
	ds_read2_b64 v[2:5], v2 offset1:1
	ds_read2_b64 v[6:9], v6 offset1:1
	v_lshl_add_u64 v[14:15], v[52:53], 0, v[36:37]
	v_cvt_pk_bf16_f32 v11, v20, v21
	s_waitcnt lgkmcnt(2)
	v_cvt_pk_bf16_f32 v12, v22, v23
	s_waitcnt lgkmcnt(1)
	v_cvt_pk_bf16_f32 v2, v2, v3
	v_cvt_pk_bf16_f32 v3, v4, v5
	s_waitcnt lgkmcnt(0)
	v_cvt_pk_bf16_f32 v4, v6, v7
	v_or_b32_e32 v6, s1, v58
	v_mul_u32_u24_e32 v6, 0xb00, v6
	v_lshlrev_b32_e32 v36, 1, v6
	v_cvt_pk_bf16_f32 v13, v24, v25
	v_cvt_pk_bf16_f32 v5, v8, v9
	v_lshl_add_u64 v[6:7], v[52:53], 0, v[36:37]
	global_store_dwordx4 v[14:15], v[10:13], off sc0 sc1
	global_store_dwordx4 v[6:7], v[2:5], off sc0 sc1
	s_waitcnt lgkmcnt(0)

.LBB0_203:
	s_andn2_b64 vcc, exec, s[0:1]
	s_cbranch_vccnz .LBB0_213
	s_add_i32 s0, s16, 0xfa80
	s_and_b32 s1, s0, 0xffff
	s_mul_i32 s1, s1, 0xba2f
	s_lshr_b32 s6, s1, 16
	s_lshr_b32 s1, s1, 22
	s_mulk_i32 s1, 0x58
	s_sub_i32 s0, s0, s1
	s_and_b32 s1, s0, 0xffff
	s_and_b32 s0, s6, 0xffc0
	v_or_b32_e32 v53, s0, v34
	s_lshl_b32 s10, s1, 7
	v_lshl_add_u64 v[2:3], v[48:49], 0, s[10:11]
	v_mul_u32_u24_e32 v36, 0x2c00, v53
	v_mad_u64_u32 v[4:5], s[6:7], v53, s40, v[2:3]
	v_lshl_add_u64 v[2:3], v[2:3], 0, v[36:37]
	v_add_co_u32_e32 v6, vcc, s41, v2
	v_cndmask_b32_e64 v36, 0, 1, s[12:13]
	s_nop 0
	v_addc_co_u32_e32 v7, vcc, 0, v3, vcc
	global_load_dwordx4 v[26:29], v[4:5], off nt
	global_load_dwordx4 v[30:33], v[6:7], off nt
	v_add_co_u32_e32 v4, vcc, s42, v2
	v_mov_b32_e32 v52, 1.0
	s_nop 0
	v_addc_co_u32_e32 v5, vcc, 0, v3, vcc
	v_add_co_u32_e32 v6, vcc, s43, v2
	v_cmp_ne_u32_e64 s[6:7], 1, v36
	s_nop 0
	v_addc_co_u32_e32 v7, vcc, 0, v3, vcc
	global_load_dwordx4 v[18:21], v[4:5], off nt
	global_load_dwordx4 v[22:25], v[6:7], off nt
	v_add_co_u32_e32 v4, vcc, s44, v2
	v_add_lshl_u32 v36, v34, s0, 2
	s_nop 0
	v_addc_co_u32_e32 v5, vcc, 0, v3, vcc
	v_add_co_u32_e32 v6, vcc, 0x6e000, v2
	v_mov_b32_e32 v59, 1.0
	s_nop 0
	v_addc_co_u32_e32 v7, vcc, 0, v3, vcc
	global_load_dwordx4 v[10:13], v[4:5], off nt
	global_load_dwordx4 v[14:17], v[6:7], off nt
	v_add_co_u32_e32 v4, vcc, 0x84000, v2
	s_nop 1
	v_addc_co_u32_e32 v5, vcc, 0, v3, vcc
	v_add_co_u32_e32 v6, vcc, 0x9a000, v2
	s_nop 1
	v_addc_co_u32_e32 v7, vcc, 0, v3, vcc
	global_load_dwordx4 v[2:5], v[4:5], off nt
	s_nop 0
	global_load_dwordx4 v[6:9], v[6:7], off nt
	s_andn2_b64 vcc, exec, s[12:13]
	s_cbranch_vccnz .LBB0_206
	v_lshlrev_b32_e32 v53, 2, v53
	global_load_dword v60, v53, s[72:73]
	global_load_dword v59, v36, s[72:73] offset:32
	s_waitcnt vmcnt(1)
	v_pk_mul_f32 v[26:27], v[26:27], v[60:61] op_sel_hi:[1,0]
	v_pk_mul_f32 v[28:29], v[28:29], v[60:61] op_sel_hi:[1,0]

.LBB0_214:
	s_andn2_b64 vcc, exec, s[0:1]
	s_cbranch_vccnz .LBB0_147
	s_mul_hi_i32 s0, s16, 0x2e8ba2e9
	s_lshr_b32 s1, s0, 31
	s_ashr_i32 s10, s0, 4
	s_add_i32 s10, s10, s1
	s_mul_i32 s0, s10, 0xfffff500
	s_lshl_b32 s6, s10, 6
	s_add_i32 s8, s20, s0
	v_or_b32_e32 v52, s6, v34
	s_ashr_i32 s9, s8, 31
	v_lshl_add_u64 v[2:3], s[8:9], 2, v[50:51]
	v_or_b32_e32 v6, 8, v52
	v_mad_i64_i32 v[4:5], s[0:1], v52, s40, v[2:3]
	v_mad_i64_i32 v[6:7], s[0:1], v6, s40, v[2:3]
	global_load_dwordx4 v[26:29], v[4:5], off nt
	global_load_dwordx4 v[30:33], v[6:7], off nt
	v_or_b32_e32 v4, 16, v52
	v_or_b32_e32 v6, 24, v52
	v_mad_i64_i32 v[4:5], s[0:1], v4, s40, v[2:3]
	v_mad_i64_i32 v[6:7], s[0:1], v6, s40, v[2:3]
	global_load_dwordx4 v[18:21], v[4:5], off nt
	global_load_dwordx4 v[22:25], v[6:7], off nt
	v_or_b32_e32 v4, 32, v52
	v_or_b32_e32 v6, 40, v52
	v_mad_i64_i32 v[4:5], s[0:1], v4, s40, v[2:3]
	v_mad_i64_i32 v[6:7], s[0:1], v6, s40, v[2:3]
	global_load_dwordx4 v[10:13], v[4:5], off nt
	global_load_dwordx4 v[14:17], v[6:7], off nt
	v_or_b32_e32 v4, 48, v52
	v_or_b32_e32 v6, 56, v52
	v_mad_i64_i32 v[4:5], s[0:1], v4, s40, v[2:3]
	v_mad_i64_i32 v[6:7], s[0:1], v6, s40, v[2:3]
	global_load_dwordx4 v[2:5], v[4:5], off nt
	s_nop 0
	global_load_dwordx4 v[6:9], v[6:7], off nt
	v_cndmask_b32_e64 v53, 0, 1, s[12:13]
	v_mov_b32_e32 v36, 1.0
	v_cmp_ne_u32_e64 s[0:1], 1, v53
	s_andn2_b64 vcc, exec, s[12:13]
	v_mov_b32_e32 v53, 1.0
	s_cbranch_vccnz .LBB0_217
	s_ashr_i32 s7, s6, 31
	v_ashrrev_i32_e32 v53, 31, v52
	v_lshl_add_u64 v[60:61], s[6:7], 0, v[34:35]
	v_lshl_add_u64 v[52:53], v[52:53], 2, s[72:73]
	v_lshl_add_u64 v[60:61], v[60:61], 2, s[72:73]
	global_load_dword v52, v[52:53], off
	s_nop 0
	global_load_dword v53, v[60:61], off offset:32
	s_waitcnt vmcnt(0)
	v_pk_mul_f32 v[26:27], v[26:27], v[52:53] op_sel_hi:[1,0]
	v_pk_mul_f32 v[28:29], v[28:29], v[52:53] op_sel_hi:[1,0]

.LBB0_557:
	s_cmpk_gt_i32 s36, 0x57f
	s_mov_b64 s[0:1], -1
	s_cbranch_scc0 .LBB0_663
	s_cmpk_gt_u32 s36, 0xaff
	s_cbranch_scc0 .LBB0_652
	s_cmpk_gt_u32 s36, 0x107f
	s_cbranch_scc0 .LBB0_649
	s_cmpk_gt_u32 s36, 0x1aff
	s_cbranch_scc0 .LBB0_598
	s_cmpk_gt_u32 s36, 0x1bff
	s_cbranch_scc0 .LBB0_595
	s_cmpk_gt_u32 s36, 0x1cff
	s_cbranch_scc0 .LBB0_592
	s_cmpk_gt_u32 s36, 0x1eff
	s_cbranch_scc0 .LBB0_589
	s_cmpk_gt_u32 s36, 0x247f
	s_cbranch_scc0 .LBB0_578
	s_cmpk_gt_u32 s36, 0x29ff
	s_cbranch_scc0 .LBB0_567
	s_add_i32 s1, s22, 0xfffac000
	s_and_b32 s0, s26, 0xfc0
	s_and_b32 s1, s1, 0x3e0
	v_or_b32_e32 v4, s0, v34
	s_lshl_b32 s8, s1, 2
	v_lshl_add_u64 v[2:3], v[52:53], 0, s[8:9]
	v_lshlrev_b32_e32 v36, 12, v4
	v_lshl_add_u64 v[26:27], v[2:3], 0, v[36:37]
	v_add_co_u32_e32 v6, vcc, s34, v26
	v_or_b32_e32 v36, s1, v34
	s_nop 0
	v_addc_co_u32_e32 v7, vcc, 0, v27, vcc
	v_add_co_u32_e32 v10, vcc, s35, v26
	global_load_dwordx4 v[2:5], v[26:27], off nt
	s_nop 0
	global_load_dwordx4 v[6:9], v[6:7], off nt
	v_addc_co_u32_e32 v11, vcc, 0, v27, vcc
	v_add_co_u32_e32 v14, vcc, s38, v26
	v_or_b32_e32 v72, s1, v74
	s_nop 0
	v_addc_co_u32_e32 v15, vcc, 0, v27, vcc
	v_add_co_u32_e32 v18, vcc, s39, v26
	global_load_dwordx4 v[10:13], v[10:11], off nt
	s_nop 0
	global_load_dwordx4 v[14:17], v[14:15], off nt
	v_addc_co_u32_e32 v19, vcc, 0, v27, vcc
	v_add_co_u32_e32 v22, vcc, s42, v26
	v_or_b32_e32 v73, s1, v75
	s_nop 0
	v_addc_co_u32_e32 v23, vcc, 0, v27, vcc
	v_add_co_u32_e32 v28, vcc, s43, v26
	global_load_dwordx4 v[18:21], v[18:19], off nt
	s_nop 0
	global_load_dwordx4 v[22:25], v[22:23], off nt
	v_addc_co_u32_e32 v29, vcc, 0, v27, vcc
	v_add_co_u32_e32 v30, vcc, s44, v26
	s_lshl_b32 s8, s0, 1
	s_nop 0
	v_addc_co_u32_e32 v31, vcc, 0, v27, vcc
	global_load_dwordx4 v[26:29], v[28:29], off nt
	s_nop 0
	global_load_dwordx4 v[30:33], v[30:31], off nt
	v_mul_u32_u24_e32 v36, 0xb00, v36
	v_mul_u32_u24_e32 v86, 0xb00, v72
	v_mul_u32_u24_e32 v88, 0xb00, v73
	v_lshl_add_u64 v[72:73], v[38:39], 0, s[8:9]
	v_lshlrev_b32_e32 v36, 1, v36
	v_lshl_add_u64 v[84:85], v[72:73], 0, v[36:37]
	v_lshlrev_b32_e32 v36, 1, v86
	v_lshl_add_u64 v[86:87], v[72:73], 0, v[36:37]
	v_lshlrev_b32_e32 v36, 1, v88
	s_waitcnt vmcnt(0)
	ds_write2_b32 v1, v2, v6 offset1:8
	ds_write2_b32 v1, v3, v7 offset0:66 offset1:74
	ds_write2_b32 v1, v4, v8 offset0:132 offset1:140
	ds_write2_b32 v1, v5, v9 offset0:198 offset1:206
	ds_write2_b32 v1, v10, v14 offset0:16 offset1:24
	ds_write2_b32 v1, v11, v15 offset0:82 offset1:90
	ds_write2_b32 v1, v12, v16 offset0:148 offset1:156
	ds_write2_b32 v1, v13, v17 offset0:214 offset1:222
	ds_write2_b32 v1, v18, v22 offset0:32 offset1:40
	ds_write2_b32 v1, v19, v23 offset0:98 offset1:106
	ds_write2_b32 v1, v20, v24 offset0:164 offset1:172
	ds_write2_b32 v1, v21, v25 offset0:230 offset1:238
	ds_write2_b32 v1, v26, v30 offset0:48 offset1:56
	ds_write2_b32 v1, v27, v31 offset0:114 offset1:122
	ds_write2_b32 v1, v28, v32 offset0:180 offset1:188
	ds_write2_b32 v1, v29, v33 offset0:246 offset1:254
	s_waitcnt lgkmcnt(0)
	ds_read2_b64 v[2:5], v77 offset1:1
	ds_read2_b64 v[6:9], v77 offset0:2 offset1:3
	ds_read2_b64 v[10:13], v78 offset1:1
	ds_read2_b64 v[14:17], v79 offset1:1
	ds_read2_b64 v[18:21], v80 offset1:1
	ds_read2_b64 v[22:25], v81 offset1:1
	ds_read2_b64 v[26:29], v82 offset1:1
	s_waitcnt lgkmcnt(6)
	v_cvt_pk_bf16_f32 v2, v2, v3
	v_cvt_pk_bf16_f32 v3, v4, v5
	s_waitcnt lgkmcnt(5)
	v_cvt_pk_bf16_f32 v4, v6, v7
	v_cvt_pk_bf16_f32 v5, v8, v9
	s_waitcnt lgkmcnt(4)
	v_cvt_pk_bf16_f32 v6, v10, v11
	v_cvt_pk_bf16_f32 v7, v12, v13
	s_waitcnt lgkmcnt(3)
	v_cvt_pk_bf16_f32 v8, v14, v15
	v_cvt_pk_bf16_f32 v9, v16, v17
	global_store_dwordx4 v[84:85], v[2:5], off
	global_store_dwordx4 v[86:87], v[6:9], off
	ds_read2_b64 v[2:5], v83 offset1:1
	s_waitcnt lgkmcnt(3)
	v_cvt_pk_bf16_f32 v10, v18, v19
	v_cvt_pk_bf16_f32 v11, v20, v21
	s_waitcnt lgkmcnt(2)
	v_cvt_pk_bf16_f32 v12, v22, v23
	v_cvt_pk_bf16_f32 v13, v24, v25
	s_waitcnt lgkmcnt(0)
	v_cvt_pk_bf16_f32 v8, v2, v3
	v_or_b32_e32 v2, s1, v76
	v_mul_u32_u24_e32 v2, 0xb00, v2
	v_lshl_add_u64 v[6:7], v[72:73], 0, v[36:37]
	v_lshlrev_b32_e32 v36, 1, v2
	global_store_dwordx4 v[6:7], v[10:13], off
	v_cvt_pk_bf16_f32 v6, v26, v27
	v_cvt_pk_bf16_f32 v7, v28, v29
	v_cvt_pk_bf16_f32 v9, v4, v5
	v_lshl_add_u64 v[2:3], v[72:73], 0, v[36:37]
	global_store_dwordx4 v[2:3], v[6:9], off
	s_waitcnt lgkmcnt(0)
	s_mov_b64 s[0:1], 0
.LBB0_567:
	s_andn2_b64 vcc, exec, s[0:1]
	s_cbranch_vccnz .LBB0_577
	s_add_i32 s0, s36, 0xdb80
	s_and_b32 s1, s0, 0xffff
	s_mul_i32 s1, s1, 0xba2f
	s_lshr_b32 s4, s1, 16
	s_lshr_b32 s1, s1, 22
	s_mulk_i32 s1, 0x58
	s_sub_i32 s0, s0, s1
	s_and_b32 s1, s0, 0xffff
	s_and_b32 s0, s4, 0xffc0
	v_or_b32_e32 v73, s0, v34
	s_lshl_b32 s8, s1, 7
	v_lshl_add_u64 v[2:3], v[54:55], 0, s[8:9]
	v_mul_u32_u24_e32 v36, 0x2c00, v73
	v_mad_u64_u32 v[4:5], s[4:5], v73, s45, v[2:3]
	v_lshl_add_u64 v[2:3], v[2:3], 0, v[36:37]
	v_add_co_u32_e32 v6, vcc, s46, v2
	v_cndmask_b32_e64 v36, 0, 1, s[10:11]
	s_nop 0
	v_addc_co_u32_e32 v7, vcc, 0, v3, vcc
	global_load_dwordx4 v[26:29], v[4:5], off nt
	global_load_dwordx4 v[30:33], v[6:7], off nt
	v_add_co_u32_e32 v4, vcc, s47, v2
	v_mov_b32_e32 v72, 1.0
	s_nop 0
	v_addc_co_u32_e32 v5, vcc, 0, v3, vcc
	v_add_co_u32_e32 v6, vcc, s48, v2
	v_cmp_ne_u32_e64 s[4:5], 1, v36
	s_nop 0
	v_addc_co_u32_e32 v7, vcc, 0, v3, vcc
	global_load_dwordx4 v[18:21], v[4:5], off nt
	global_load_dwordx4 v[22:25], v[6:7], off nt
	v_add_co_u32_e32 v4, vcc, s49, v2
	v_add_lshl_u32 v36, v34, s0, 2
	s_nop 0
	v_addc_co_u32_e32 v5, vcc, 0, v3, vcc
	v_add_co_u32_e32 v6, vcc, 0x6e000, v2
	v_mov_b32_e32 v84, 1.0
	s_nop 0
	v_addc_co_u32_e32 v7, vcc, 0, v3, vcc
	global_load_dwordx4 v[10:13], v[4:5], off nt
	global_load_dwordx4 v[14:17], v[6:7], off nt
	v_add_co_u32_e32 v4, vcc, 0x84000, v2
	s_nop 1
	v_addc_co_u32_e32 v5, vcc, 0, v3, vcc
	v_add_co_u32_e32 v6, vcc, 0x9a000, v2
	s_nop 1
	v_addc_co_u32_e32 v7, vcc, 0, v3, vcc
	global_load_dwordx4 v[2:5], v[4:5], off nt
	s_nop 0
	global_load_dwordx4 v[6:9], v[6:7], off nt
	s_andn2_b64 vcc, exec, s[10:11]
	s_cbranch_vccnz .LBB0_570
	v_readlane_b32 s64, v253, 4
	v_lshlrev_b32_e32 v73, 2, v73
	v_readlane_b32 s65, v253, 5
	s_nop 4
	global_load_dword v86, v73, s[64:65]
	global_load_dword v84, v36, s[64:65] offset:32
	v_readlane_b32 s66, v253, 6
	v_readlane_b32 s67, v253, 7
	v_readlane_b32 s68, v253, 8
	v_readlane_b32 s69, v253, 9
	v_readlane_b32 s70, v253, 10
	v_readlane_b32 s71, v253, 11
	s_waitcnt vmcnt(0)
	v_pk_mul_f32 v[26:27], v[26:27], v[86:87] op_sel_hi:[1,0]
	v_pk_mul_f32 v[28:29], v[28:29], v[86:87] op_sel_hi:[1,0]

.LBB0_578:
	s_andn2_b64 vcc, exec, s[0:1]
	s_cbranch_vccnz .LBB0_588
	s_add_i32 s0, s36, 0xe100
	s_and_b32 s1, s0, 0xffff
	s_mul_i32 s1, s1, 0xba2f
	s_lshr_b32 s4, s1, 16
	s_lshr_b32 s1, s1, 22
	s_mulk_i32 s1, 0x58
	s_sub_i32 s0, s0, s1
	s_and_b32 s1, s0, 0xffff
	s_and_b32 s0, s4, 0xffc0
	v_or_b32_e32 v73, s0, v34
	s_lshl_b32 s8, s1, 7
	v_lshl_add_u64 v[2:3], v[56:57], 0, s[8:9]
	v_mul_u32_u24_e32 v36, 0x2c00, v73
	v_mad_u64_u32 v[4:5], s[4:5], v73, s45, v[2:3]
	v_lshl_add_u64 v[2:3], v[2:3], 0, v[36:37]
	v_add_co_u32_e32 v6, vcc, s46, v2
	v_cndmask_b32_e64 v36, 0, 1, s[10:11]
	s_nop 0
	v_addc_co_u32_e32 v7, vcc, 0, v3, vcc
	global_load_dwordx4 v[26:29], v[4:5], off nt
	global_load_dwordx4 v[30:33], v[6:7], off nt
	v_add_co_u32_e32 v4, vcc, s47, v2
	v_mov_b32_e32 v72, 1.0
	s_nop 0
	v_addc_co_u32_e32 v5, vcc, 0, v3, vcc
	v_add_co_u32_e32 v6, vcc, s48, v2
	v_cmp_ne_u32_e64 s[4:5], 1, v36
	s_nop 0
	v_addc_co_u32_e32 v7, vcc, 0, v3, vcc
	global_load_dwordx4 v[18:21], v[4:5], off nt
	global_load_dwordx4 v[22:25], v[6:7], off nt
	v_add_co_u32_e32 v4, vcc, s49, v2
	v_add_lshl_u32 v36, v34, s0, 2
	s_nop 0
	v_addc_co_u32_e32 v5, vcc, 0, v3, vcc
	v_add_co_u32_e32 v6, vcc, 0x6e000, v2
	v_mov_b32_e32 v84, 1.0
	s_nop 0
	v_addc_co_u32_e32 v7, vcc, 0, v3, vcc
	global_load_dwordx4 v[10:13], v[4:5], off nt
	global_load_dwordx4 v[14:17], v[6:7], off nt
	v_add_co_u32_e32 v4, vcc, 0x84000, v2
	s_nop 1
	v_addc_co_u32_e32 v5, vcc, 0, v3, vcc
	v_add_co_u32_e32 v6, vcc, 0x9a000, v2
	s_nop 1
	v_addc_co_u32_e32 v7, vcc, 0, v3, vcc
	global_load_dwordx4 v[2:5], v[4:5], off nt
	s_nop 0
	global_load_dwordx4 v[6:9], v[6:7], off nt
	s_andn2_b64 vcc, exec, s[10:11]
	s_cbranch_vccnz .LBB0_581
	v_readlane_b32 s64, v253, 4
	v_lshlrev_b32_e32 v73, 2, v73
	v_readlane_b32 s65, v253, 5
	s_nop 4
	global_load_dword v86, v73, s[64:65]
	global_load_dword v84, v36, s[64:65] offset:32
	v_readlane_b32 s66, v253, 6
	v_readlane_b32 s67, v253, 7
	v_readlane_b32 s68, v253, 8
	v_readlane_b32 s69, v253, 9
	v_readlane_b32 s70, v253, 10
	v_readlane_b32 s71, v253, 11
	s_waitcnt vmcnt(0)
	v_pk_mul_f32 v[26:27], v[26:27], v[86:87] op_sel_hi:[1,0]
	v_pk_mul_f32 v[28:29], v[28:29], v[86:87] op_sel_hi:[1,0]

.LBB0_589:
	s_andn2_b64 vcc, exec, s[0:1]
	s_cbranch_vccnz .LBB0_591
	s_add_i32 s0, s26, 0x1a00
	s_add_i32 s1, s22, 0xfffc6000
	s_and_b32 s0, s0, 0xfc0
	s_and_b32 s1, s1, 0x3e0
	v_or_b32_e32 v4, s0, v34
	s_lshl_b32 s8, s1, 2
	v_lshl_add_u64 v[2:3], v[58:59], 0, s[8:9]
	v_lshlrev_b32_e32 v36, 12, v4
	v_lshl_add_u64 v[26:27], v[2:3], 0, v[36:37]
	v_add_co_u32_e32 v6, vcc, s34, v26
	v_or_b32_e32 v36, s1, v34
	s_nop 0
	v_addc_co_u32_e32 v7, vcc, 0, v27, vcc
	v_add_co_u32_e32 v10, vcc, s35, v26
	global_load_dwordx4 v[2:5], v[26:27], off nt
	s_nop 0
	global_load_dwordx4 v[6:9], v[6:7], off nt
	v_addc_co_u32_e32 v11, vcc, 0, v27, vcc
	v_add_co_u32_e32 v14, vcc, s38, v26
	s_lshl_b32 s8, s0, 1
	s_nop 0
	v_addc_co_u32_e32 v15, vcc, 0, v27, vcc
	v_add_co_u32_e32 v18, vcc, s39, v26
	global_load_dwordx4 v[10:13], v[10:11], off nt
	s_nop 0
	global_load_dwordx4 v[14:17], v[14:15], off nt
	v_addc_co_u32_e32 v19, vcc, 0, v27, vcc
	v_add_co_u32_e32 v22, vcc, s42, v26
	v_or_b32_e32 v86, s1, v74
	s_nop 0
	v_addc_co_u32_e32 v23, vcc, 0, v27, vcc
	v_add_co_u32_e32 v28, vcc, s43, v26
	global_load_dwordx4 v[18:21], v[18:19], off nt
	s_nop 0
	global_load_dwordx4 v[22:25], v[22:23], off nt
	v_addc_co_u32_e32 v29, vcc, 0, v27, vcc
	v_add_co_u32_e32 v30, vcc, s44, v26
	v_lshl_add_u64 v[72:73], v[42:43], 0, s[8:9]
	s_nop 0
	v_addc_co_u32_e32 v31, vcc, 0, v27, vcc
	global_load_dwordx4 v[26:29], v[28:29], off nt
	s_nop 0
	global_load_dwordx4 v[30:33], v[30:31], off nt
	v_lshlrev_b32_e32 v36, 11, v36
	v_or_b32_e32 v88, s1, v75
	v_lshl_add_u64 v[84:85], v[72:73], 0, v[36:37]
	v_lshlrev_b32_e32 v36, 11, v86
	v_lshl_add_u64 v[86:87], v[72:73], 0, v[36:37]
	v_lshlrev_b32_e32 v36, 11, v88
	v_lshl_add_u64 v[88:89], v[72:73], 0, v[36:37]
	s_waitcnt vmcnt(0)
	ds_write2_b32 v1, v2, v6 offset1:8
	ds_write2_b32 v1, v3, v7 offset0:66 offset1:74
	ds_write2_b32 v1, v4, v8 offset0:132 offset1:140
	ds_write2_b32 v1, v5, v9 offset0:198 offset1:206
	ds_write2_b32 v1, v10, v14 offset0:16 offset1:24
	ds_write2_b32 v1, v11, v15 offset0:82 offset1:90
	ds_write2_b32 v1, v12, v16 offset0:148 offset1:156
	ds_write2_b32 v1, v13, v17 offset0:214 offset1:222
	ds_write2_b32 v1, v18, v22 offset0:32 offset1:40
	ds_write2_b32 v1, v19, v23 offset0:98 offset1:106
	ds_write2_b32 v1, v20, v24 offset0:164 offset1:172
	ds_write2_b32 v1, v21, v25 offset0:230 offset1:238
	ds_write2_b32 v1, v26, v30 offset0:48 offset1:56
	ds_write2_b32 v1, v27, v31 offset0:114 offset1:122
	ds_write2_b32 v1, v28, v32 offset0:180 offset1:188
	ds_write2_b32 v1, v29, v33 offset0:246 offset1:254
	s_waitcnt lgkmcnt(0)
	ds_read2_b64 v[2:5], v77 offset1:1
	ds_read2_b64 v[6:9], v77 offset0:2 offset1:3
	ds_read2_b64 v[10:13], v78 offset1:1
	ds_read2_b64 v[14:17], v79 offset1:1
	ds_read2_b64 v[18:21], v80 offset1:1
	ds_read2_b64 v[22:25], v81 offset1:1
	ds_read2_b64 v[26:29], v82 offset1:1
	ds_read2_b64 v[30:33], v83 offset1:1
	s_waitcnt lgkmcnt(7)
	v_cvt_pk_bf16_f32 v2, v2, v3
	v_cvt_pk_bf16_f32 v3, v4, v5
	s_waitcnt lgkmcnt(6)
	v_cvt_pk_bf16_f32 v4, v6, v7
	v_cvt_pk_bf16_f32 v5, v8, v9
	s_waitcnt lgkmcnt(5)
	v_cvt_pk_bf16_f32 v6, v10, v11
	v_cvt_pk_bf16_f32 v7, v12, v13
	s_waitcnt lgkmcnt(4)
	v_cvt_pk_bf16_f32 v8, v14, v15
	v_cvt_pk_bf16_f32 v9, v16, v17
	s_waitcnt lgkmcnt(3)
	v_cvt_pk_bf16_f32 v10, v18, v19
	v_cvt_pk_bf16_f32 v11, v20, v21
	s_waitcnt lgkmcnt(2)
	v_cvt_pk_bf16_f32 v12, v22, v23
	v_cvt_pk_bf16_f32 v13, v24, v25
	global_store_dwordx4 v[84:85], v[2:5], off
	global_store_dwordx4 v[86:87], v[6:9], off
	global_store_dwordx4 v[88:89], v[10:13], off
	s_waitcnt lgkmcnt(1)
	v_cvt_pk_bf16_f32 v2, v26, v27
	v_or_b32_e32 v6, s1, v76
	v_lshlrev_b32_e32 v36, 11, v6
	v_cvt_pk_bf16_f32 v3, v28, v29
	s_waitcnt lgkmcnt(0)
	v_cvt_pk_bf16_f32 v4, v30, v31
	v_cvt_pk_bf16_f32 v5, v32, v33
	v_lshl_add_u64 v[6:7], v[72:73], 0, v[36:37]
	global_store_dwordx4 v[6:7], v[2:5], off
	s_waitcnt lgkmcnt(0)

.LBB0_592:
	s_andn2_b64 vcc, exec, s[0:1]
	s_cbranch_vccnz .LBB0_594
	s_add_i32 s0, s26, 0x1c00
	s_add_i32 s1, s22, 0xfffc8000
	s_and_b32 s0, s0, 0xfc0
	s_and_b32 s1, s1, 0x3e0
	v_or_b32_e32 v4, s0, v34
	s_lshl_b32 s8, s1, 2
	v_lshl_add_u64 v[2:3], v[60:61], 0, s[8:9]
	v_lshlrev_b32_e32 v36, 12, v4
	v_lshl_add_u64 v[26:27], v[2:3], 0, v[36:37]
	v_add_co_u32_e32 v6, vcc, s34, v26
	s_bitset1_b32 s1, 10
	s_nop 0
	v_addc_co_u32_e32 v7, vcc, 0, v27, vcc
	v_add_co_u32_e32 v10, vcc, s35, v26
	global_load_dwordx4 v[2:5], v[26:27], off nt
	s_nop 0
	global_load_dwordx4 v[6:9], v[6:7], off nt
	v_addc_co_u32_e32 v11, vcc, 0, v27, vcc
	v_add_co_u32_e32 v14, vcc, s38, v26
	s_lshl_b32 s8, s0, 1
	s_nop 0
	v_addc_co_u32_e32 v15, vcc, 0, v27, vcc
	v_add_co_u32_e32 v18, vcc, s39, v26
	global_load_dwordx4 v[10:13], v[10:11], off nt
	s_nop 0
	global_load_dwordx4 v[14:17], v[14:15], off nt
	v_addc_co_u32_e32 v19, vcc, 0, v27, vcc
	v_add_co_u32_e32 v22, vcc, s42, v26
	v_or_b32_e32 v36, s1, v34
	s_nop 0
	v_addc_co_u32_e32 v23, vcc, 0, v27, vcc
	v_add_co_u32_e32 v28, vcc, s43, v26
	global_load_dwordx4 v[18:21], v[18:19], off nt
	s_nop 0
	global_load_dwordx4 v[22:25], v[22:23], off nt
	v_addc_co_u32_e32 v29, vcc, 0, v27, vcc
	v_add_co_u32_e32 v30, vcc, s44, v26
	v_or_b32_e32 v86, s1, v74
	s_nop 0
	v_addc_co_u32_e32 v31, vcc, 0, v27, vcc
	global_load_dwordx4 v[26:29], v[28:29], off nt
	s_nop 0
	global_load_dwordx4 v[30:33], v[30:31], off nt
	v_lshl_add_u64 v[72:73], v[44:45], 0, s[8:9]
	v_lshlrev_b32_e32 v36, 10, v36
	v_or_b32_e32 v88, s1, v75
	v_lshl_add_u64 v[84:85], v[72:73], 0, v[36:37]
	v_lshlrev_b32_e32 v36, 10, v86
	v_lshl_add_u64 v[86:87], v[72:73], 0, v[36:37]
	v_lshlrev_b32_e32 v36, 10, v88
	s_waitcnt vmcnt(0)
	ds_write2_b32 v1, v2, v6 offset1:8
	ds_write2_b32 v1, v3, v7 offset0:66 offset1:74
	ds_write2_b32 v1, v4, v8 offset0:132 offset1:140
	ds_write2_b32 v1, v5, v9 offset0:198 offset1:206
	ds_write2_b32 v1, v10, v14 offset0:16 offset1:24
	ds_write2_b32 v1, v11, v15 offset0:82 offset1:90
	ds_write2_b32 v1, v12, v16 offset0:148 offset1:156
	ds_write2_b32 v1, v13, v17 offset0:214 offset1:222
	ds_write2_b32 v1, v18, v22 offset0:32 offset1:40
	ds_write2_b32 v1, v19, v23 offset0:98 offset1:106
	ds_write2_b32 v1, v20, v24 offset0:164 offset1:172
	ds_write2_b32 v1, v21, v25 offset0:230 offset1:238
	ds_write2_b32 v1, v26, v30 offset0:48 offset1:56
	ds_write2_b32 v1, v27, v31 offset0:114 offset1:122
	ds_write2_b32 v1, v28, v32 offset0:180 offset1:188
	ds_write2_b32 v1, v29, v33 offset0:246 offset1:254
	s_waitcnt lgkmcnt(0)
	ds_read2_b64 v[2:5], v77 offset1:1
	ds_read2_b64 v[6:9], v77 offset0:2 offset1:3
	ds_read2_b64 v[10:13], v78 offset1:1
	ds_read2_b64 v[14:17], v79 offset1:1
	ds_read2_b64 v[18:21], v80 offset1:1
	ds_read2_b64 v[22:25], v81 offset1:1
	ds_read2_b64 v[26:29], v82 offset1:1
	ds_read2_b64 v[30:33], v83 offset1:1
	s_waitcnt lgkmcnt(7)
	v_cvt_pk_bf16_f32 v2, v2, v3
	v_cvt_pk_bf16_f32 v3, v4, v5
	s_waitcnt lgkmcnt(6)
	v_cvt_pk_bf16_f32 v4, v6, v7
	v_cvt_pk_bf16_f32 v5, v8, v9
	s_waitcnt lgkmcnt(5)
	v_cvt_pk_bf16_f32 v6, v10, v11
	v_cvt_pk_bf16_f32 v7, v12, v13
	s_waitcnt lgkmcnt(4)
	v_cvt_pk_bf16_f32 v8, v14, v15
	v_cvt_pk_bf16_f32 v9, v16, v17
	global_store_dwordx4 v[84:85], v[2:5], off
	global_store_dwordx4 v[86:87], v[6:9], off
	s_waitcnt lgkmcnt(3)
	v_cvt_pk_bf16_f32 v10, v18, v19
	v_cvt_pk_bf16_f32 v11, v20, v21
	v_or_b32_e32 v6, s1, v76
	s_waitcnt lgkmcnt(2)
	v_cvt_pk_bf16_f32 v12, v22, v23
	v_cvt_pk_bf16_f32 v13, v24, v25
	v_lshl_add_u64 v[2:3], v[72:73], 0, v[36:37]
	v_lshlrev_b32_e32 v36, 10, v6
	global_store_dwordx4 v[2:3], v[10:13], off
	s_waitcnt lgkmcnt(1)
	v_cvt_pk_bf16_f32 v2, v26, v27
	v_cvt_pk_bf16_f32 v3, v28, v29
	s_waitcnt lgkmcnt(0)
	v_cvt_pk_bf16_f32 v4, v30, v31
	v_cvt_pk_bf16_f32 v5, v32, v33
	v_lshl_add_u64 v[6:7], v[72:73], 0, v[36:37]
	global_store_dwordx4 v[6:7], v[2:5], off
	s_waitcnt lgkmcnt(0)

.LBB0_595:
	s_andn2_b64 vcc, exec, s[0:1]
	s_cbranch_vccnz .LBB0_597
	s_add_i32 s0, s26, 0x1e00
	s_add_i32 s1, s22, 0xfffca000
	s_and_b32 s0, s0, 0xfc0
	s_and_b32 s1, s1, 0x3e0
	v_or_b32_e32 v4, s0, v34
	s_lshl_b32 s8, s1, 2
	v_lshl_add_u64 v[2:3], v[62:63], 0, s[8:9]
	v_lshlrev_b32_e32 v36, 12, v4
	v_lshl_add_u64 v[26:27], v[2:3], 0, v[36:37]
	v_add_co_u32_e32 v6, vcc, s34, v26
	v_or_b32_e32 v36, s1, v34
	s_nop 0
	v_addc_co_u32_e32 v7, vcc, 0, v27, vcc
	v_add_co_u32_e32 v10, vcc, s35, v26
	global_load_dwordx4 v[2:5], v[26:27], off nt
	s_nop 0
	global_load_dwordx4 v[6:9], v[6:7], off nt
	v_addc_co_u32_e32 v11, vcc, 0, v27, vcc
	v_add_co_u32_e32 v14, vcc, s38, v26
	s_lshl_b32 s8, s0, 1
	s_nop 0
	v_addc_co_u32_e32 v15, vcc, 0, v27, vcc
	v_add_co_u32_e32 v18, vcc, s39, v26
	global_load_dwordx4 v[10:13], v[10:11], off nt
	s_nop 0
	global_load_dwordx4 v[14:17], v[14:15], off nt
	v_addc_co_u32_e32 v19, vcc, 0, v27, vcc
	v_add_co_u32_e32 v22, vcc, s42, v26
	v_or_b32_e32 v86, s1, v74
	s_nop 0
	v_addc_co_u32_e32 v23, vcc, 0, v27, vcc
	v_add_co_u32_e32 v28, vcc, s43, v26
	global_load_dwordx4 v[18:21], v[18:19], off nt
	s_nop 0
	global_load_dwordx4 v[22:25], v[22:23], off nt
	v_addc_co_u32_e32 v29, vcc, 0, v27, vcc
	v_add_co_u32_e32 v30, vcc, s44, v26
	v_lshl_add_u64 v[72:73], v[44:45], 0, s[8:9]
	s_nop 0
	v_addc_co_u32_e32 v31, vcc, 0, v27, vcc
	global_load_dwordx4 v[26:29], v[28:29], off nt
	s_nop 0
	global_load_dwordx4 v[30:33], v[30:31], off nt
	v_lshlrev_b32_e32 v36, 10, v36
	v_or_b32_e32 v88, s1, v75
	v_lshl_add_u64 v[84:85], v[72:73], 0, v[36:37]
	v_lshlrev_b32_e32 v36, 10, v86
	v_lshl_add_u64 v[86:87], v[72:73], 0, v[36:37]
	v_lshlrev_b32_e32 v36, 10, v88
	v_lshl_add_u64 v[88:89], v[72:73], 0, v[36:37]
	s_waitcnt vmcnt(0)
	ds_write2_b32 v1, v2, v6 offset1:8
	ds_write2_b32 v1, v3, v7 offset0:66 offset1:74
	ds_write2_b32 v1, v4, v8 offset0:132 offset1:140
	ds_write2_b32 v1, v5, v9 offset0:198 offset1:206
	ds_write2_b32 v1, v10, v14 offset0:16 offset1:24
	ds_write2_b32 v1, v11, v15 offset0:82 offset1:90
	ds_write2_b32 v1, v12, v16 offset0:148 offset1:156
	ds_write2_b32 v1, v13, v17 offset0:214 offset1:222
	ds_write2_b32 v1, v18, v22 offset0:32 offset1:40
	ds_write2_b32 v1, v19, v23 offset0:98 offset1:106
	ds_write2_b32 v1, v20, v24 offset0:164 offset1:172
	ds_write2_b32 v1, v21, v25 offset0:230 offset1:238
	ds_write2_b32 v1, v26, v30 offset0:48 offset1:56
	ds_write2_b32 v1, v27, v31 offset0:114 offset1:122
	ds_write2_b32 v1, v28, v32 offset0:180 offset1:188
	ds_write2_b32 v1, v29, v33 offset0:246 offset1:254
	s_waitcnt lgkmcnt(0)
	ds_read2_b64 v[2:5], v77 offset1:1
	ds_read2_b64 v[6:9], v77 offset0:2 offset1:3
	ds_read2_b64 v[10:13], v78 offset1:1
	ds_read2_b64 v[14:17], v79 offset1:1
	ds_read2_b64 v[18:21], v80 offset1:1
	ds_read2_b64 v[22:25], v81 offset1:1
	ds_read2_b64 v[26:29], v82 offset1:1
	ds_read2_b64 v[30:33], v83 offset1:1
	s_waitcnt lgkmcnt(7)
	v_cvt_pk_bf16_f32 v2, v2, v3
	v_cvt_pk_bf16_f32 v3, v4, v5
	s_waitcnt lgkmcnt(6)
	v_cvt_pk_bf16_f32 v4, v6, v7
	v_cvt_pk_bf16_f32 v5, v8, v9
	s_waitcnt lgkmcnt(5)
	v_cvt_pk_bf16_f32 v6, v10, v11
	v_cvt_pk_bf16_f32 v7, v12, v13
	s_waitcnt lgkmcnt(4)
	v_cvt_pk_bf16_f32 v8, v14, v15
	v_cvt_pk_bf16_f32 v9, v16, v17
	s_waitcnt lgkmcnt(3)
	v_cvt_pk_bf16_f32 v10, v18, v19
	v_cvt_pk_bf16_f32 v11, v20, v21
	s_waitcnt lgkmcnt(2)
	v_cvt_pk_bf16_f32 v12, v22, v23
	v_cvt_pk_bf16_f32 v13, v24, v25
	global_store_dwordx4 v[84:85], v[2:5], off
	global_store_dwordx4 v[86:87], v[6:9], off
	global_store_dwordx4 v[88:89], v[10:13], off
	s_waitcnt lgkmcnt(1)
	v_cvt_pk_bf16_f32 v2, v26, v27
	v_or_b32_e32 v6, s1, v76
	v_lshlrev_b32_e32 v36, 10, v6
	v_cvt_pk_bf16_f32 v3, v28, v29
	s_waitcnt lgkmcnt(0)
	v_cvt_pk_bf16_f32 v4, v30, v31
	v_cvt_pk_bf16_f32 v5, v32, v33
	v_lshl_add_u64 v[6:7], v[72:73], 0, v[36:37]
	global_store_dwordx4 v[6:7], v[2:5], off
	s_waitcnt lgkmcnt(0)

.LBB0_598:
	s_andn2_b64 vcc, exec, s[0:1]
	s_cbranch_vccnz .LBB0_648
	s_add_i32 s0, s36, 0xef80
	s_bfe_u32 s1, s0, 0xd0003
	s_mulk_i32 s1, 0xc31
	s_lshr_b32 s1, s1, 16
	s_mul_i32 s4, s1, 0xa8
	s_sub_i32 s18, s0, s4
	s_lshl_b32 s16, s1, 6
	v_or_b32_e32 v73, s16, v34
	s_lshl_b32 s0, s18, 7
	s_and_b32 s8, s0, 0x3ff80
	v_mul_u32_u24_e32 v4, 0x1500, v73
	v_lshl_add_u64 v[2:3], v[64:65], 0, s[8:9]
	v_lshlrev_b32_e32 v36, 2, v4
	v_lshl_add_u64 v[2:3], v[2:3], 0, v[36:37]
	v_add_co_u32_e32 v4, vcc, s50, v2
	v_cndmask_b32_e64 v36, 0, 1, s[12:13]
	s_nop 0
	v_addc_co_u32_e32 v5, vcc, 0, v3, vcc
	global_load_dwordx4 v[26:29], v[2:3], off nt
	global_load_dwordx4 v[30:33], v[4:5], off nt
	v_add_co_u32_e32 v4, vcc, s51, v2
	v_mov_b32_e32 v72, 1.0
	s_nop 0
	v_addc_co_u32_e32 v5, vcc, 0, v3, vcc
	v_add_co_u32_e32 v6, vcc, s52, v2
	v_cmp_ne_u32_e64 s[4:5], 1, v36
	s_nop 0
	v_addc_co_u32_e32 v7, vcc, 0, v3, vcc
	global_load_dwordx4 v[18:21], v[4:5], off nt
	global_load_dwordx4 v[22:25], v[6:7], off nt
	v_add_co_u32_e32 v4, vcc, s53, v2
	v_add_lshl_u32 v36, v34, s16, 2
	s_nop 0
	v_addc_co_u32_e32 v5, vcc, 0, v3, vcc
	v_add_co_u32_e32 v6, vcc, 0xd2000, v2
	v_mov_b32_e32 v84, 1.0
	s_nop 0
	v_addc_co_u32_e32 v7, vcc, 0, v3, vcc
	global_load_dwordx4 v[10:13], v[4:5], off nt
	global_load_dwordx4 v[14:17], v[6:7], off nt
	v_add_co_u32_e32 v4, vcc, 0xfc000, v2
	s_nop 1
	v_addc_co_u32_e32 v5, vcc, 0, v3, vcc
	v_add_co_u32_e32 v6, vcc, 0x126000, v2
	s_nop 1
	v_addc_co_u32_e32 v7, vcc, 0, v3, vcc
	global_load_dwordx4 v[2:5], v[4:5], off nt
	s_nop 0
	global_load_dwordx4 v[6:9], v[6:7], off nt
	s_andn2_b64 vcc, exec, s[12:13]
	s_cbranch_vccnz .LBB0_601
	v_lshlrev_b32_e32 v73, 2, v73
	global_load_dword v86, v73, s[80:81]
	global_load_dword v84, v36, s[80:81] offset:32
	s_waitcnt vmcnt(0)
	v_pk_mul_f32 v[26:27], v[26:27], v[86:87] op_sel_hi:[1,0]
	v_pk_mul_f32 v[28:29], v[28:29], v[86:87] op_sel_hi:[1,0]

.LBB0_649:
	s_andn2_b64 vcc, exec, s[0:1]
	s_cbranch_vccnz .LBB0_651
	s_add_i32 s0, s26, 0x3e00
	s_add_i32 s1, s22, 0xfffea000
	s_and_b32 s0, s0, 0xfc0
	s_and_b32 s1, s1, 0x3e0
	v_or_b32_e32 v4, s0, v34
	s_lshl_b32 s8, s1, 2
	v_lshl_add_u64 v[2:3], v[66:67], 0, s[8:9]
	v_lshlrev_b32_e32 v36, 12, v4
	v_lshl_add_u64 v[26:27], v[2:3], 0, v[36:37]
	v_add_co_u32_e32 v6, vcc, s34, v26
	v_or_b32_e32 v36, s1, v34
	s_nop 0
	v_addc_co_u32_e32 v7, vcc, 0, v27, vcc
	v_add_co_u32_e32 v10, vcc, s35, v26
	global_load_dwordx4 v[2:5], v[26:27], off nt
	s_nop 0
	global_load_dwordx4 v[6:9], v[6:7], off nt
	v_addc_co_u32_e32 v11, vcc, 0, v27, vcc
	v_add_co_u32_e32 v14, vcc, s38, v26
	v_or_b32_e32 v72, s1, v74
	s_nop 0
	v_addc_co_u32_e32 v15, vcc, 0, v27, vcc
	v_add_co_u32_e32 v18, vcc, s39, v26
	global_load_dwordx4 v[10:13], v[10:11], off nt
	s_nop 0
	global_load_dwordx4 v[14:17], v[14:15], off nt
	v_addc_co_u32_e32 v19, vcc, 0, v27, vcc
	v_add_co_u32_e32 v22, vcc, s42, v26
	v_or_b32_e32 v73, s1, v75
	s_nop 0
	v_addc_co_u32_e32 v23, vcc, 0, v27, vcc
	v_add_co_u32_e32 v28, vcc, s43, v26
	global_load_dwordx4 v[18:21], v[18:19], off nt
	s_nop 0
	global_load_dwordx4 v[22:25], v[22:23], off nt
	v_addc_co_u32_e32 v29, vcc, 0, v27, vcc
	v_add_co_u32_e32 v30, vcc, s44, v26
	s_lshl_b32 s8, s0, 1
	s_nop 0
	v_addc_co_u32_e32 v31, vcc, 0, v27, vcc
	global_load_dwordx4 v[26:29], v[28:29], off nt
	s_nop 0
	global_load_dwordx4 v[30:33], v[30:31], off nt
	v_mul_u32_u24_e32 v36, 0xb00, v36
	v_mul_u32_u24_e32 v86, 0xb00, v72
	v_mul_u32_u24_e32 v88, 0xb00, v73
	v_lshl_add_u64 v[72:73], v[48:49], 0, s[8:9]
	v_lshlrev_b32_e32 v36, 1, v36
	v_lshl_add_u64 v[84:85], v[72:73], 0, v[36:37]
	v_lshlrev_b32_e32 v36, 1, v86
	v_lshl_add_u64 v[86:87], v[72:73], 0, v[36:37]
	v_lshlrev_b32_e32 v36, 1, v88
	s_waitcnt vmcnt(0)
	ds_write2_b32 v1, v2, v6 offset1:8
	ds_write2_b32 v1, v3, v7 offset0:66 offset1:74
	ds_write2_b32 v1, v4, v8 offset0:132 offset1:140
	ds_write2_b32 v1, v5, v9 offset0:198 offset1:206
	ds_write2_b32 v1, v10, v14 offset0:16 offset1:24
	ds_write2_b32 v1, v11, v15 offset0:82 offset1:90
	ds_write2_b32 v1, v12, v16 offset0:148 offset1:156
	ds_write2_b32 v1, v13, v17 offset0:214 offset1:222
	ds_write2_b32 v1, v18, v22 offset0:32 offset1:40
	ds_write2_b32 v1, v19, v23 offset0:98 offset1:106
	ds_write2_b32 v1, v20, v24 offset0:164 offset1:172
	ds_write2_b32 v1, v21, v25 offset0:230 offset1:238
	ds_write2_b32 v1, v26, v30 offset0:48 offset1:56
	ds_write2_b32 v1, v27, v31 offset0:114 offset1:122
	ds_write2_b32 v1, v28, v32 offset0:180 offset1:188
	ds_write2_b32 v1, v29, v33 offset0:246 offset1:254
	s_waitcnt lgkmcnt(0)
	ds_read2_b64 v[2:5], v77 offset1:1
	ds_read2_b64 v[6:9], v77 offset0:2 offset1:3
	ds_read2_b64 v[10:13], v78 offset1:1
	ds_read2_b64 v[14:17], v79 offset1:1
	ds_read2_b64 v[18:21], v80 offset1:1
	ds_read2_b64 v[22:25], v81 offset1:1
	ds_read2_b64 v[26:29], v82 offset1:1
	s_waitcnt lgkmcnt(6)
	v_cvt_pk_bf16_f32 v2, v2, v3
	v_cvt_pk_bf16_f32 v3, v4, v5
	s_waitcnt lgkmcnt(5)
	v_cvt_pk_bf16_f32 v4, v6, v7
	v_cvt_pk_bf16_f32 v5, v8, v9
	s_waitcnt lgkmcnt(4)
	v_cvt_pk_bf16_f32 v6, v10, v11
	v_cvt_pk_bf16_f32 v7, v12, v13
	s_waitcnt lgkmcnt(3)
	v_cvt_pk_bf16_f32 v8, v14, v15
	v_cvt_pk_bf16_f32 v9, v16, v17
	global_store_dwordx4 v[84:85], v[2:5], off
	global_store_dwordx4 v[86:87], v[6:9], off
	ds_read2_b64 v[2:5], v83 offset1:1
	s_waitcnt lgkmcnt(3)
	v_cvt_pk_bf16_f32 v10, v18, v19
	v_cvt_pk_bf16_f32 v11, v20, v21
	s_waitcnt lgkmcnt(2)
	v_cvt_pk_bf16_f32 v12, v22, v23
	v_cvt_pk_bf16_f32 v13, v24, v25
	s_waitcnt lgkmcnt(0)
	v_cvt_pk_bf16_f32 v8, v2, v3
	v_or_b32_e32 v2, s1, v76
	v_mul_u32_u24_e32 v2, 0xb00, v2
	v_lshl_add_u64 v[6:7], v[72:73], 0, v[36:37]
	v_lshlrev_b32_e32 v36, 1, v2
	global_store_dwordx4 v[6:7], v[10:13], off
	v_cvt_pk_bf16_f32 v6, v26, v27
	v_cvt_pk_bf16_f32 v7, v28, v29
	v_cvt_pk_bf16_f32 v9, v4, v5
	v_lshl_add_u64 v[2:3], v[72:73], 0, v[36:37]
	global_store_dwordx4 v[2:3], v[6:9], off
	s_waitcnt lgkmcnt(0)

.LBB0_652:
	s_andn2_b64 vcc, exec, s[0:1]
	s_cbranch_vccnz .LBB0_662
	s_add_i32 s0, s36, 0xfa80
	s_and_b32 s1, s0, 0xffff
	s_mul_i32 s1, s1, 0xba2f
	s_lshr_b32 s4, s1, 16
	s_lshr_b32 s1, s1, 22
	s_mulk_i32 s1, 0x58
	s_sub_i32 s0, s0, s1
	s_and_b32 s1, s0, 0xffff
	s_and_b32 s0, s4, 0xffc0
	v_or_b32_e32 v73, s0, v34
	s_lshl_b32 s8, s1, 7
	v_lshl_add_u64 v[2:3], v[68:69], 0, s[8:9]
	v_mul_u32_u24_e32 v36, 0x2c00, v73
	v_mad_u64_u32 v[4:5], s[4:5], v73, s45, v[2:3]
	v_lshl_add_u64 v[2:3], v[2:3], 0, v[36:37]
	v_add_co_u32_e32 v6, vcc, s46, v2
	v_cndmask_b32_e64 v36, 0, 1, s[14:15]
	s_nop 0
	v_addc_co_u32_e32 v7, vcc, 0, v3, vcc
	global_load_dwordx4 v[26:29], v[4:5], off nt
	global_load_dwordx4 v[30:33], v[6:7], off nt
	v_add_co_u32_e32 v4, vcc, s47, v2
	v_mov_b32_e32 v72, 1.0
	s_nop 0
	v_addc_co_u32_e32 v5, vcc, 0, v3, vcc
	v_add_co_u32_e32 v6, vcc, s48, v2
	v_cmp_ne_u32_e64 s[4:5], 1, v36
	s_nop 0
	v_addc_co_u32_e32 v7, vcc, 0, v3, vcc
	global_load_dwordx4 v[18:21], v[4:5], off nt
	global_load_dwordx4 v[22:25], v[6:7], off nt
	v_add_co_u32_e32 v4, vcc, s49, v2
	v_add_lshl_u32 v36, v34, s0, 2
	s_nop 0
	v_addc_co_u32_e32 v5, vcc, 0, v3, vcc
	v_add_co_u32_e32 v6, vcc, 0x6e000, v2
	v_mov_b32_e32 v84, 1.0
	s_nop 0
	v_addc_co_u32_e32 v7, vcc, 0, v3, vcc
	global_load_dwordx4 v[10:13], v[4:5], off nt
	global_load_dwordx4 v[14:17], v[6:7], off nt
	v_add_co_u32_e32 v4, vcc, 0x84000, v2
	s_nop 1
	v_addc_co_u32_e32 v5, vcc, 0, v3, vcc
	v_add_co_u32_e32 v6, vcc, 0x9a000, v2
	s_nop 1
	v_addc_co_u32_e32 v7, vcc, 0, v3, vcc
	global_load_dwordx4 v[2:5], v[4:5], off nt
	s_nop 0
	global_load_dwordx4 v[6:9], v[6:7], off nt
	s_andn2_b64 vcc, exec, s[14:15]
	s_cbranch_vccnz .LBB0_655
	v_lshlrev_b32_e32 v73, 2, v73
	global_load_dword v86, v73, s[72:73]
	global_load_dword v84, v36, s[72:73] offset:32
	s_waitcnt vmcnt(0)
	v_pk_mul_f32 v[26:27], v[26:27], v[86:87] op_sel_hi:[1,0]
	v_pk_mul_f32 v[28:29], v[28:29], v[86:87] op_sel_hi:[1,0]

.LBB0_663:
	s_andn2_b64 vcc, exec, s[0:1]
	s_cbranch_vccnz .LBB0_556
	s_mul_hi_i32 s0, s36, 0x2e8ba2e9
	s_lshr_b32 s1, s0, 31
	s_ashr_i32 s8, s0, 4
	s_add_i32 s8, s8, s1
	s_mul_i32 s0, s8, 0xfffff500
	s_lshl_b32 s4, s8, 6
	s_add_i32 s6, s22, s0
	v_or_b32_e32 v72, s4, v34
	s_ashr_i32 s7, s6, 31
	v_lshl_add_u64 v[2:3], s[6:7], 2, v[70:71]
	v_or_b32_e32 v6, 8, v72
	v_mad_i64_i32 v[4:5], s[0:1], v72, s45, v[2:3]
	v_mad_i64_i32 v[6:7], s[0:1], v6, s45, v[2:3]
	global_load_dwordx4 v[26:29], v[4:5], off nt
	global_load_dwordx4 v[30:33], v[6:7], off nt
	v_or_b32_e32 v4, 16, v72
	v_or_b32_e32 v6, 24, v72
	v_mad_i64_i32 v[4:5], s[0:1], v4, s45, v[2:3]
	v_mad_i64_i32 v[6:7], s[0:1], v6, s45, v[2:3]
	global_load_dwordx4 v[18:21], v[4:5], off nt
	global_load_dwordx4 v[22:25], v[6:7], off nt
	v_or_b32_e32 v4, 32, v72
	v_or_b32_e32 v6, 40, v72
	v_mad_i64_i32 v[4:5], s[0:1], v4, s45, v[2:3]
	v_mad_i64_i32 v[6:7], s[0:1], v6, s45, v[2:3]
	global_load_dwordx4 v[10:13], v[4:5], off nt
	global_load_dwordx4 v[14:17], v[6:7], off nt
	v_or_b32_e32 v4, 48, v72
	v_or_b32_e32 v6, 56, v72
	v_mad_i64_i32 v[4:5], s[0:1], v4, s45, v[2:3]
	v_mad_i64_i32 v[6:7], s[0:1], v6, s45, v[2:3]
	global_load_dwordx4 v[2:5], v[4:5], off nt
	s_nop 0
	global_load_dwordx4 v[6:9], v[6:7], off nt
	v_cndmask_b32_e64 v73, 0, 1, s[14:15]
	v_mov_b32_e32 v36, 1.0
	v_cmp_ne_u32_e64 s[0:1], 1, v73
	s_andn2_b64 vcc, exec, s[14:15]
	v_mov_b32_e32 v73, 1.0
	s_cbranch_vccnz .LBB0_666
	s_ashr_i32 s5, s4, 31
	v_ashrrev_i32_e32 v73, 31, v72
	v_lshl_add_u64 v[84:85], s[4:5], 0, v[34:35]
	v_lshl_add_u64 v[72:73], v[72:73], 2, s[72:73]
	v_lshl_add_u64 v[84:85], v[84:85], 2, s[72:73]
	global_load_dword v72, v[72:73], off
	s_nop 0
	global_load_dword v73, v[84:85], off offset:32
	s_waitcnt vmcnt(0)
	v_pk_mul_f32 v[26:27], v[26:27], v[72:73] op_sel_hi:[1,0]
	v_pk_mul_f32 v[28:29], v[28:29], v[72:73] op_sel_hi:[1,0]
